# P1 scale epilogue (both store-policy paths) hand-scheduled like P6: partial-sum loads up front in two batches, counted waits, stores never waited on
# baseline (speedup 1.0000x reference)
; __device__ __forceinline__ unsigned pk2(float lo, float hi) { f32x2 v = {lo, hi}; bf16x2_t b = __builtin_convertvector(v, bf16x2_t); return __builtin_bit_cast(unsigned, b); }
; __device__ __forceinline__ float ss_total(const float* ss, int row) { const f32x4* sp = (const f32x4*)(ss + (size_t)row * 16); const f32x4 a = sp[0], b = sp[1], c = sp[2], d = sp[3];
;     return (((a[0] + a[1]) + (a[2] + a[3])) + ((b[0] + b[1]) + (b[2] + b[3]))) + (((c[0] + c[1]) + (c[2] + c[3])) + ((d[0] + d[1]) + (d[2] + d[3]))); }
;     __device__ __forceinline__ void operator()(const f32x4 (&acc)[2][2][4][2], const pg8::Unit& u, int wr, int wc, int fr, int fq) const {
;         const int row0 = u.pm * 256 + wr * 64 + fr, col0 = u.pn * 256 + wc * 32 + 8 * fq;
; #pragma unroll
;         for (int ai = 0; ai < 2; ++ai)
; #pragma unroll
;             for (int m = 0; m < 4; ++m) { const int row = row0 + ai * 128 + m * 16; const float rs = rsqrtf(ss_total(ss, row) * (1.f / 1024.f) + EPS);
;                 bf16_t* rowp = O + (size_t)row * ldc + col0;
; #pragma unroll
;                 for (int bj = 0; bj < 2; ++bj) { const f32x4 v0 = acc[ai][bj][m][0] * rs, v1 = acc[ai][bj][m][1] * rs;
;                     u32x4 w; w.x = pk2(v0[0], v0[1]); w.y = pk2(v0[2], v0[3]); w.z = pk2(v1[0], v1[1]); w.w = pk2(v1[2], v1[3]);
;                     *(u32x4*)(rowp + bj * 128) = w; } }
;     }
.LBB0_133:
	s_cmp_ge_u32 s82, 16
	s_cbranch_scc1 .Lp1_epi_nt
	v_lshl_add_u32 v246, s83, 8, v159
	v_lshl_or_b32 v247, s82, 8, v161
	v_lshlrev_b32_e32 v152, 6, v246
	v_mov_b32_e32 v153, 0
	v_lshl_add_u64 v[152:153], s[22:23], 0, v[152:153]
	s_mov_b32 s4, 0x3a00
	v_mul_lo_u32 v164, v246, s4
	v_lshl_add_u32 v164, v247, 1, v164
	v_mov_b32_e32 v165, 0
	v_lshl_add_u64 v[154:155], s[14:15], 0, v[164:165]
	global_load_dwordx4 v[164:167], v[152:153], off
	global_load_dwordx4 v[168:171], v[152:153], off offset:16
	global_load_dwordx4 v[172:175], v[152:153], off offset:32
	global_load_dwordx4 v[176:179], v[152:153], off offset:48
	s_mov_b64 s[4:5], 0x400
	v_lshl_add_u64 v[152:153], v[152:153], 0, s[4:5]
	global_load_dwordx4 v[180:183], v[152:153], off
	global_load_dwordx4 v[184:187], v[152:153], off offset:16
	global_load_dwordx4 v[204:207], v[152:153], off offset:32
	global_load_dwordx4 v[208:211], v[152:153], off offset:48
	s_mov_b64 s[4:5], 0x400
	v_lshl_add_u64 v[152:153], v[152:153], 0, s[4:5]
	global_load_dwordx4 v[212:215], v[152:153], off
	global_load_dwordx4 v[216:219], v[152:153], off offset:16
	global_load_dwordx4 v[220:223], v[152:153], off offset:32
	global_load_dwordx4 v[224:227], v[152:153], off offset:48
	s_mov_b64 s[4:5], 0x400
	v_lshl_add_u64 v[152:153], v[152:153], 0, s[4:5]
	global_load_dwordx4 v[228:231], v[152:153], off
	global_load_dwordx4 v[232:235], v[152:153], off offset:16
	global_load_dwordx4 v[236:239], v[152:153], off offset:32
	global_load_dwordx4 v[240:243], v[152:153], off offset:48
	s_mov_b64 s[4:5], 0x1400
	v_lshl_add_u64 v[152:153], v[152:153], 0, s[4:5]
	s_waitcnt vmcnt(0)
	v_add_f32_e32 v164, v164, v165
	v_add_f32_e32 v168, v168, v169
	v_add_f32_e32 v172, v172, v173
	v_add_f32_e32 v176, v176, v177
	v_add_f32_e32 v166, v166, v167
	v_add_f32_e32 v170, v170, v171
	v_add_f32_e32 v174, v174, v175
	v_add_f32_e32 v178, v178, v179
	v_add_f32_e32 v164, v164, v166
	v_add_f32_e32 v168, v168, v170
	v_add_f32_e32 v172, v172, v174
	v_add_f32_e32 v176, v176, v178
	v_add_f32_e32 v164, v164, v168
	v_add_f32_e32 v172, v172, v176
	v_add_f32_e32 v164, v164, v172
	v_fmamk_f32 v164, v164, 0x3a800000, v190
	v_cmp_gt_f32_e32 vcc, s66, v164
	v_mul_f32_e32 v245, 0x4b800000, v164
	s_nop 1
	v_cndmask_b32_e32 v164, v164, v245, vcc
	v_rsq_f32_e32 v164, v164
	s_nop 0
	v_mul_f32_e32 v245, 0x45800000, v164
	v_cndmask_b32_e32 v156, v164, v245, vcc
	v_add_f32_e32 v180, v180, v181
	v_add_f32_e32 v184, v184, v185
	v_add_f32_e32 v204, v204, v205
	v_add_f32_e32 v208, v208, v209
	v_add_f32_e32 v182, v182, v183
	v_add_f32_e32 v186, v186, v187
	v_add_f32_e32 v206, v206, v207
	v_add_f32_e32 v210, v210, v211
	v_add_f32_e32 v180, v180, v182
	v_add_f32_e32 v184, v184, v186
	v_add_f32_e32 v204, v204, v206
	v_add_f32_e32 v208, v208, v210
	v_add_f32_e32 v180, v180, v184
	v_add_f32_e32 v204, v204, v208
	v_add_f32_e32 v180, v180, v204
	v_fmamk_f32 v180, v180, 0x3a800000, v190
	v_cmp_gt_f32_e32 vcc, s66, v180
	v_mul_f32_e32 v245, 0x4b800000, v180
	s_nop 1
	v_cndmask_b32_e32 v180, v180, v245, vcc
	v_rsq_f32_e32 v180, v180
	s_nop 0
	v_mul_f32_e32 v245, 0x45800000, v180
	v_cndmask_b32_e32 v157, v180, v245, vcc
	v_add_f32_e32 v212, v212, v213
	v_add_f32_e32 v216, v216, v217
	v_add_f32_e32 v220, v220, v221
	v_add_f32_e32 v224, v224, v225
	v_add_f32_e32 v214, v214, v215
	v_add_f32_e32 v218, v218, v219
	v_add_f32_e32 v222, v222, v223
	v_add_f32_e32 v226, v226, v227
	v_add_f32_e32 v212, v212, v214
	v_add_f32_e32 v216, v216, v218
	v_add_f32_e32 v220, v220, v222
	v_add_f32_e32 v224, v224, v226
	v_add_f32_e32 v212, v212, v216
	v_add_f32_e32 v220, v220, v224
	v_add_f32_e32 v212, v212, v220
	v_fmamk_f32 v212, v212, 0x3a800000, v190
	v_cmp_gt_f32_e32 vcc, s66, v212
	v_mul_f32_e32 v245, 0x4b800000, v212
	s_nop 1
	v_cndmask_b32_e32 v212, v212, v245, vcc
	v_rsq_f32_e32 v212, v212
	s_nop 0
	v_mul_f32_e32 v245, 0x45800000, v212
	v_cndmask_b32_e32 v163, v212, v245, vcc
	v_add_f32_e32 v228, v228, v229
	v_add_f32_e32 v232, v232, v233
	v_add_f32_e32 v236, v236, v237
	v_add_f32_e32 v240, v240, v241
	v_add_f32_e32 v230, v230, v231
	v_add_f32_e32 v234, v234, v235
	v_add_f32_e32 v238, v238, v239
	v_add_f32_e32 v242, v242, v243
	v_add_f32_e32 v228, v228, v230
	v_add_f32_e32 v232, v232, v234
	v_add_f32_e32 v236, v236, v238
	v_add_f32_e32 v240, v240, v242
	v_add_f32_e32 v228, v228, v232
	v_add_f32_e32 v236, v236, v240
	v_add_f32_e32 v228, v228, v236
	v_fmamk_f32 v228, v228, 0x3a800000, v190
	v_cmp_gt_f32_e32 vcc, s66, v228
	v_mul_f32_e32 v245, 0x4b800000, v228
	s_nop 1
	v_cndmask_b32_e32 v228, v228, v245, vcc
	v_rsq_f32_e32 v228, v228
	s_nop 0
	v_mul_f32_e32 v245, 0x45800000, v228
	v_cndmask_b32_e32 v244, v228, v245, vcc
	global_load_dwordx4 v[164:167], v[152:153], off
	global_load_dwordx4 v[168:171], v[152:153], off offset:16
	global_load_dwordx4 v[172:175], v[152:153], off offset:32
	global_load_dwordx4 v[176:179], v[152:153], off offset:48
	s_mov_b64 s[4:5], 0x400
	v_lshl_add_u64 v[152:153], v[152:153], 0, s[4:5]
	global_load_dwordx4 v[180:183], v[152:153], off
	global_load_dwordx4 v[184:187], v[152:153], off offset:16
	global_load_dwordx4 v[204:207], v[152:153], off offset:32
	global_load_dwordx4 v[208:211], v[152:153], off offset:48
	s_mov_b64 s[4:5], 0x400
	v_lshl_add_u64 v[152:153], v[152:153], 0, s[4:5]
	global_load_dwordx4 v[212:215], v[152:153], off
	global_load_dwordx4 v[216:219], v[152:153], off offset:16
	global_load_dwordx4 v[220:223], v[152:153], off offset:32
	global_load_dwordx4 v[224:227], v[152:153], off offset:48
	s_mov_b64 s[4:5], 0x400
	v_lshl_add_u64 v[152:153], v[152:153], 0, s[4:5]
	global_load_dwordx4 v[228:231], v[152:153], off
	global_load_dwordx4 v[232:235], v[152:153], off offset:16
; __device__ __forceinline__ unsigned pk2(float lo, float hi) { f32x2 v = {lo, hi}; bf16x2_t b = __builtin_convertvector(v, bf16x2_t); return __builtin_bit_cast(unsigned, b); }
;     __device__ __forceinline__ void operator()(const f32x4 (&acc)[2][2][4][2], const pg8::Unit& u, int wr, int wc, int fr, int fq) const {
;         const int row0 = u.pm * 256 + wr * 64 + fr, col0 = u.pn * 256 + wc * 32 + 8 * fq;
; #pragma unroll
;         for (int ai = 0; ai < 2; ++ai)
; #pragma unroll
;             for (int m = 0; m < 4; ++m) { const int row = row0 + ai * 128 + m * 16; const float rs = rsqrtf(ss_total(ss, row) * (1.f / 1024.f) + EPS);
;                 bf16_t* rowp = O + (size_t)row * ldc + col0;
; #pragma unroll
;                 for (int bj = 0; bj < 2; ++bj) { const f32x4 v0 = acc[ai][bj][m][0] * rs, v1 = acc[ai][bj][m][1] * rs;
;                     u32x4 w; w.x = pk2(v0[0], v0[1]); w.y = pk2(v0[2], v0[3]); w.z = pk2(v1[0], v1[1]); w.w = pk2(v1[2], v1[3]);
;                     *(u32x4*)(rowp + bj * 128) = w; } }
;     }
	global_load_dwordx4 v[236:239], v[152:153], off offset:32
	global_load_dwordx4 v[240:243], v[152:153], off offset:48
	v_mul_f32_e32 v126, v126, v156
	v_mul_f32_e32 v127, v127, v156
	v_mul_f32_e32 v128, v128, v156
	v_mul_f32_e32 v129, v129, v156
	v_mul_f32_e32 v122, v122, v156
	v_mul_f32_e32 v123, v123, v156
	v_mul_f32_e32 v124, v124, v156
	v_mul_f32_e32 v125, v125, v156
	v_cvt_pk_bf16_f32 v126, v126, v127
	v_cvt_pk_bf16_f32 v127, v128, v129
	v_cvt_pk_bf16_f32 v128, v122, v123
	v_cvt_pk_bf16_f32 v129, v124, v125
	global_store_dwordx4 v[154:155], v[126:129], off
	v_mul_f32_e32 v118, v118, v156
	v_mul_f32_e32 v119, v119, v156
	v_mul_f32_e32 v120, v120, v156
	v_mul_f32_e32 v121, v121, v156
	v_mul_f32_e32 v114, v114, v156
	v_mul_f32_e32 v115, v115, v156
	v_mul_f32_e32 v116, v116, v156
	v_mul_f32_e32 v117, v117, v156
	v_cvt_pk_bf16_f32 v118, v118, v119
	v_cvt_pk_bf16_f32 v119, v120, v121
	v_cvt_pk_bf16_f32 v120, v114, v115
	v_cvt_pk_bf16_f32 v121, v116, v117
	global_store_dwordx4 v[154:155], v[118:121], off offset:256
	s_mov_b64 s[4:5], 0x3a000
	v_lshl_add_u64 v[154:155], v[154:155], 0, s[4:5]
	v_mul_f32_e32 v110, v110, v157
	v_mul_f32_e32 v111, v111, v157
	v_mul_f32_e32 v112, v112, v157
	v_mul_f32_e32 v113, v113, v157
	v_mul_f32_e32 v106, v106, v157
	v_mul_f32_e32 v107, v107, v157
	v_mul_f32_e32 v108, v108, v157
	v_mul_f32_e32 v109, v109, v157
	v_cvt_pk_bf16_f32 v110, v110, v111
	v_cvt_pk_bf16_f32 v111, v112, v113
	v_cvt_pk_bf16_f32 v112, v106, v107
	v_cvt_pk_bf16_f32 v113, v108, v109
	global_store_dwordx4 v[154:155], v[110:113], off
	v_mul_f32_e32 v102, v102, v157
	v_mul_f32_e32 v103, v103, v157
	v_mul_f32_e32 v104, v104, v157
	v_mul_f32_e32 v105, v105, v157
	v_mul_f32_e32 v98, v98, v157
	v_mul_f32_e32 v99, v99, v157
	v_mul_f32_e32 v100, v100, v157
	v_mul_f32_e32 v101, v101, v157
	v_cvt_pk_bf16_f32 v102, v102, v103
	v_cvt_pk_bf16_f32 v103, v104, v105
	v_cvt_pk_bf16_f32 v104, v98, v99
	v_cvt_pk_bf16_f32 v105, v100, v101
	global_store_dwordx4 v[154:155], v[102:105], off offset:256
	s_mov_b64 s[4:5], 0x3a000
	v_lshl_add_u64 v[154:155], v[154:155], 0, s[4:5]
	v_mul_f32_e32 v94, v94, v163
	v_mul_f32_e32 v95, v95, v163
	v_mul_f32_e32 v96, v96, v163
	v_mul_f32_e32 v97, v97, v163
	v_mul_f32_e32 v90, v90, v163
	v_mul_f32_e32 v91, v91, v163
	v_mul_f32_e32 v92, v92, v163
	v_mul_f32_e32 v93, v93, v163
	v_cvt_pk_bf16_f32 v94, v94, v95
	v_cvt_pk_bf16_f32 v95, v96, v97
	v_cvt_pk_bf16_f32 v96, v90, v91
	v_cvt_pk_bf16_f32 v97, v92, v93
	global_store_dwordx4 v[154:155], v[94:97], off
	v_mul_f32_e32 v86, v86, v163
	v_mul_f32_e32 v87, v87, v163
	v_mul_f32_e32 v88, v88, v163
	v_mul_f32_e32 v89, v89, v163
	v_mul_f32_e32 v82, v82, v163
	v_mul_f32_e32 v83, v83, v163
	v_mul_f32_e32 v84, v84, v163
	v_mul_f32_e32 v85, v85, v163
	v_cvt_pk_bf16_f32 v86, v86, v87
	v_cvt_pk_bf16_f32 v87, v88, v89
	v_cvt_pk_bf16_f32 v88, v82, v83
	v_cvt_pk_bf16_f32 v89, v84, v85
	global_store_dwordx4 v[154:155], v[86:89], off offset:256
	s_mov_b64 s[4:5], 0x3a000
	v_lshl_add_u64 v[154:155], v[154:155], 0, s[4:5]
	v_mul_f32_e32 v78, v78, v244
	v_mul_f32_e32 v79, v79, v244
	v_mul_f32_e32 v80, v80, v244
	v_mul_f32_e32 v81, v81, v244
	v_mul_f32_e32 v74, v74, v244
	v_mul_f32_e32 v75, v75, v244
	v_mul_f32_e32 v76, v76, v244
	v_mul_f32_e32 v77, v77, v244
	v_cvt_pk_bf16_f32 v78, v78, v79
	v_cvt_pk_bf16_f32 v79, v80, v81
	v_cvt_pk_bf16_f32 v80, v74, v75
	v_cvt_pk_bf16_f32 v81, v76, v77
	global_store_dwordx4 v[154:155], v[78:81], off
	v_mul_f32_e32 v70, v70, v244
	v_mul_f32_e32 v71, v71, v244
	v_mul_f32_e32 v72, v72, v244
	v_mul_f32_e32 v73, v73, v244
	v_mul_f32_e32 v66, v66, v244
	v_mul_f32_e32 v67, v67, v244
	v_mul_f32_e32 v68, v68, v244
	v_mul_f32_e32 v69, v69, v244
	v_cvt_pk_bf16_f32 v70, v70, v71
	v_cvt_pk_bf16_f32 v71, v72, v73
	v_cvt_pk_bf16_f32 v72, v66, v67
	v_cvt_pk_bf16_f32 v73, v68, v69
	global_store_dwordx4 v[154:155], v[70:73], off offset:256
	s_mov_b64 s[4:5], 0x122000
	v_lshl_add_u64 v[154:155], v[154:155], 0, s[4:5]
	s_waitcnt vmcnt(8)
; __device__ __forceinline__ unsigned pk2(float lo, float hi) { f32x2 v = {lo, hi}; bf16x2_t b = __builtin_convertvector(v, bf16x2_t); return __builtin_bit_cast(unsigned, b); }
; __device__ __forceinline__ float ss_total(const float* ss, int row) { const f32x4* sp = (const f32x4*)(ss + (size_t)row * 16); const f32x4 a = sp[0], b = sp[1], c = sp[2], d = sp[3];
;     return (((a[0] + a[1]) + (a[2] + a[3])) + ((b[0] + b[1]) + (b[2] + b[3]))) + (((c[0] + c[1]) + (c[2] + c[3])) + ((d[0] + d[1]) + (d[2] + d[3]))); }
;     __device__ __forceinline__ void operator()(const f32x4 (&acc)[2][2][4][2], const pg8::Unit& u, int wr, int wc, int fr, int fq) const {
;         const int row0 = u.pm * 256 + wr * 64 + fr, col0 = u.pn * 256 + wc * 32 + 8 * fq;
; #pragma unroll
;         for (int ai = 0; ai < 2; ++ai)
; #pragma unroll
;             for (int m = 0; m < 4; ++m) { const int row = row0 + ai * 128 + m * 16; const float rs = rsqrtf(ss_total(ss, row) * (1.f / 1024.f) + EPS);
;                 bf16_t* rowp = O + (size_t)row * ldc + col0;
; #pragma unroll
;                 for (int bj = 0; bj < 2; ++bj) { const f32x4 v0 = acc[ai][bj][m][0] * rs, v1 = acc[ai][bj][m][1] * rs;
;                     u32x4 w; w.x = pk2(v0[0], v0[1]); w.y = pk2(v0[2], v0[3]); w.z = pk2(v1[0], v1[1]); w.w = pk2(v1[2], v1[3]);
;                     *(u32x4*)(rowp + bj * 128) = w; } }
;     }
	v_add_f32_e32 v164, v164, v165
	v_add_f32_e32 v168, v168, v169
	v_add_f32_e32 v172, v172, v173
	v_add_f32_e32 v176, v176, v177
	v_add_f32_e32 v166, v166, v167
	v_add_f32_e32 v170, v170, v171
	v_add_f32_e32 v174, v174, v175
	v_add_f32_e32 v178, v178, v179
	v_add_f32_e32 v164, v164, v166
	v_add_f32_e32 v168, v168, v170
	v_add_f32_e32 v172, v172, v174
	v_add_f32_e32 v176, v176, v178
	v_add_f32_e32 v164, v164, v168
	v_add_f32_e32 v172, v172, v176
	v_add_f32_e32 v164, v164, v172
	v_fmamk_f32 v164, v164, 0x3a800000, v190
	v_cmp_gt_f32_e32 vcc, s66, v164
	v_mul_f32_e32 v245, 0x4b800000, v164
	s_nop 1
	v_cndmask_b32_e32 v164, v164, v245, vcc
	v_rsq_f32_e32 v164, v164
	s_nop 0
	v_mul_f32_e32 v245, 0x45800000, v164
	v_cndmask_b32_e32 v156, v164, v245, vcc
	v_add_f32_e32 v180, v180, v181
	v_add_f32_e32 v184, v184, v185
	v_add_f32_e32 v204, v204, v205
	v_add_f32_e32 v208, v208, v209
	v_add_f32_e32 v182, v182, v183
	v_add_f32_e32 v186, v186, v187
	v_add_f32_e32 v206, v206, v207
	v_add_f32_e32 v210, v210, v211
	v_add_f32_e32 v180, v180, v182
	v_add_f32_e32 v184, v184, v186
	v_add_f32_e32 v204, v204, v206
	v_add_f32_e32 v208, v208, v210
	v_add_f32_e32 v180, v180, v184
	v_add_f32_e32 v204, v204, v208
	v_add_f32_e32 v180, v180, v204
	v_fmamk_f32 v180, v180, 0x3a800000, v190
	v_cmp_gt_f32_e32 vcc, s66, v180
	v_mul_f32_e32 v245, 0x4b800000, v180
	s_nop 1
	v_cndmask_b32_e32 v180, v180, v245, vcc
	v_rsq_f32_e32 v180, v180
	s_nop 0
	v_mul_f32_e32 v245, 0x45800000, v180
	v_cndmask_b32_e32 v157, v180, v245, vcc
	v_add_f32_e32 v212, v212, v213
	v_add_f32_e32 v216, v216, v217
	v_add_f32_e32 v220, v220, v221
	v_add_f32_e32 v224, v224, v225
	v_add_f32_e32 v214, v214, v215
	v_add_f32_e32 v218, v218, v219
	v_add_f32_e32 v222, v222, v223
	v_add_f32_e32 v226, v226, v227
	v_add_f32_e32 v212, v212, v214
	v_add_f32_e32 v216, v216, v218
	v_add_f32_e32 v220, v220, v222
	v_add_f32_e32 v224, v224, v226
	v_add_f32_e32 v212, v212, v216
	v_add_f32_e32 v220, v220, v224
	v_add_f32_e32 v212, v212, v220
	v_fmamk_f32 v212, v212, 0x3a800000, v190
	v_cmp_gt_f32_e32 vcc, s66, v212
	v_mul_f32_e32 v245, 0x4b800000, v212
	s_nop 1
	v_cndmask_b32_e32 v212, v212, v245, vcc
	v_rsq_f32_e32 v212, v212
	s_nop 0
	v_mul_f32_e32 v245, 0x45800000, v212
	v_cndmask_b32_e32 v163, v212, v245, vcc
	v_add_f32_e32 v228, v228, v229
	v_add_f32_e32 v232, v232, v233
	v_add_f32_e32 v236, v236, v237
	v_add_f32_e32 v240, v240, v241
	v_add_f32_e32 v230, v230, v231
	v_add_f32_e32 v234, v234, v235
	v_add_f32_e32 v238, v238, v239
	v_add_f32_e32 v242, v242, v243
	v_add_f32_e32 v228, v228, v230
	v_add_f32_e32 v232, v232, v234
	v_add_f32_e32 v236, v236, v238
	v_add_f32_e32 v240, v240, v242
	v_add_f32_e32 v228, v228, v232
	v_add_f32_e32 v236, v236, v240
	v_add_f32_e32 v228, v228, v236
	v_fmamk_f32 v228, v228, 0x3a800000, v190
	v_cmp_gt_f32_e32 vcc, s66, v228
	v_mul_f32_e32 v245, 0x4b800000, v228
	s_nop 1
	v_cndmask_b32_e32 v228, v228, v245, vcc
	v_rsq_f32_e32 v228, v228
	s_nop 0
	v_mul_f32_e32 v245, 0x45800000, v228
	v_cndmask_b32_e32 v244, v228, v245, vcc
	v_mul_f32_e32 v62, v62, v156
	v_mul_f32_e32 v63, v63, v156
	v_mul_f32_e32 v64, v64, v156
	v_mul_f32_e32 v65, v65, v156
	v_mul_f32_e32 v58, v58, v156
	v_mul_f32_e32 v59, v59, v156
	v_mul_f32_e32 v60, v60, v156
	v_mul_f32_e32 v61, v61, v156
	v_cvt_pk_bf16_f32 v62, v62, v63
	v_cvt_pk_bf16_f32 v63, v64, v65
	v_cvt_pk_bf16_f32 v64, v58, v59
	v_cvt_pk_bf16_f32 v65, v60, v61
	global_store_dwordx4 v[154:155], v[62:65], off
	v_mul_f32_e32 v54, v54, v156
	v_mul_f32_e32 v55, v55, v156
	v_mul_f32_e32 v56, v56, v156
	v_mul_f32_e32 v57, v57, v156
	v_mul_f32_e32 v50, v50, v156
	v_mul_f32_e32 v51, v51, v156
	v_mul_f32_e32 v52, v52, v156
	v_mul_f32_e32 v53, v53, v156
	v_cvt_pk_bf16_f32 v54, v54, v55
	v_cvt_pk_bf16_f32 v55, v56, v57
	v_cvt_pk_bf16_f32 v56, v50, v51
	v_cvt_pk_bf16_f32 v57, v52, v53
	global_store_dwordx4 v[154:155], v[54:57], off offset:256
	s_mov_b64 s[4:5], 0x3a000
	v_lshl_add_u64 v[154:155], v[154:155], 0, s[4:5]
	v_mul_f32_e32 v46, v46, v157
	v_mul_f32_e32 v47, v47, v157
	v_mul_f32_e32 v48, v48, v157
	v_mul_f32_e32 v49, v49, v157
	v_mul_f32_e32 v42, v42, v157
	v_mul_f32_e32 v43, v43, v157
	v_mul_f32_e32 v44, v44, v157
	v_mul_f32_e32 v45, v45, v157
	v_cvt_pk_bf16_f32 v46, v46, v47
	v_cvt_pk_bf16_f32 v47, v48, v49
	v_cvt_pk_bf16_f32 v48, v42, v43
	v_cvt_pk_bf16_f32 v49, v44, v45
	global_store_dwordx4 v[154:155], v[46:49], off
	v_mul_f32_e32 v38, v38, v157
	v_mul_f32_e32 v39, v39, v157
	v_mul_f32_e32 v40, v40, v157
	v_mul_f32_e32 v41, v41, v157
	v_mul_f32_e32 v34, v34, v157
	v_mul_f32_e32 v35, v35, v157
	v_mul_f32_e32 v36, v36, v157
	v_mul_f32_e32 v37, v37, v157
	v_cvt_pk_bf16_f32 v38, v38, v39
	v_cvt_pk_bf16_f32 v39, v40, v41
	v_cvt_pk_bf16_f32 v40, v34, v35
	v_cvt_pk_bf16_f32 v41, v36, v37
	global_store_dwordx4 v[154:155], v[38:41], off offset:256
	s_mov_b64 s[4:5], 0x3a000
	v_lshl_add_u64 v[154:155], v[154:155], 0, s[4:5]
	v_mul_f32_e32 v30, v30, v163
	v_mul_f32_e32 v31, v31, v163
	v_mul_f32_e32 v32, v32, v163
	v_mul_f32_e32 v33, v33, v163
	v_mul_f32_e32 v26, v26, v163
	v_mul_f32_e32 v27, v27, v163
	v_mul_f32_e32 v28, v28, v163
	v_mul_f32_e32 v29, v29, v163
	v_cvt_pk_bf16_f32 v30, v30, v31
	v_cvt_pk_bf16_f32 v31, v32, v33
	v_cvt_pk_bf16_f32 v32, v26, v27
	v_cvt_pk_bf16_f32 v33, v28, v29
	global_store_dwordx4 v[154:155], v[30:33], off
	v_mul_f32_e32 v22, v22, v163
	v_mul_f32_e32 v23, v23, v163
	v_mul_f32_e32 v24, v24, v163
	v_mul_f32_e32 v25, v25, v163
	v_mul_f32_e32 v18, v18, v163
	v_mul_f32_e32 v19, v19, v163
	v_mul_f32_e32 v20, v20, v163
	v_mul_f32_e32 v21, v21, v163
	v_cvt_pk_bf16_f32 v22, v22, v23
	v_cvt_pk_bf16_f32 v23, v24, v25
	v_cvt_pk_bf16_f32 v24, v18, v19
	v_cvt_pk_bf16_f32 v25, v20, v21
	global_store_dwordx4 v[154:155], v[22:25], off offset:256
	s_mov_b64 s[4:5], 0x3a000
	v_lshl_add_u64 v[154:155], v[154:155], 0, s[4:5]
	v_mul_f32_e32 v14, v14, v244
	v_mul_f32_e32 v15, v15, v244
	v_mul_f32_e32 v16, v16, v244
	v_mul_f32_e32 v17, v17, v244
	v_mul_f32_e32 v10, v10, v244
	v_mul_f32_e32 v11, v11, v244
	v_mul_f32_e32 v12, v12, v244
	v_mul_f32_e32 v13, v13, v244
	v_cvt_pk_bf16_f32 v14, v14, v15
	v_cvt_pk_bf16_f32 v15, v16, v17
	v_cvt_pk_bf16_f32 v16, v10, v11
	v_cvt_pk_bf16_f32 v17, v12, v13
	global_store_dwordx4 v[154:155], v[14:17], off
	v_mul_f32_e32 v6, v6, v244
	v_mul_f32_e32 v7, v7, v244
	v_mul_f32_e32 v8, v8, v244
	v_mul_f32_e32 v9, v9, v244
	v_mul_f32_e32 v2, v2, v244
	v_mul_f32_e32 v3, v3, v244
	v_mul_f32_e32 v4, v4, v244
	v_mul_f32_e32 v5, v5, v244
	v_cvt_pk_bf16_f32 v6, v6, v7
	v_cvt_pk_bf16_f32 v7, v8, v9
	v_cvt_pk_bf16_f32 v8, v2, v3
	v_cvt_pk_bf16_f32 v9, v4, v5
	global_store_dwordx4 v[154:155], v[6:9], off offset:256
	v_readlane_b32 s84, v250, 44
	s_mov_b64 s[4:5], -1
	s_andn2_b64 vcc, exec, s[38:39]

; __device__ __forceinline__ unsigned pk2(float lo, float hi) { f32x2 v = {lo, hi}; bf16x2_t b = __builtin_convertvector(v, bf16x2_t); return __builtin_bit_cast(unsigned, b); }
; __device__ __forceinline__ float ss_total(const float* ss, int row) { const f32x4* sp = (const f32x4*)(ss + (size_t)row * 16); const f32x4 a = sp[0], b = sp[1], c = sp[2], d = sp[3];
;     return (((a[0] + a[1]) + (a[2] + a[3])) + ((b[0] + b[1]) + (b[2] + b[3]))) + (((c[0] + c[1]) + (c[2] + c[3])) + ((d[0] + d[1]) + (d[2] + d[3]))); }
;     __device__ __forceinline__ void operator()(const f32x4 (&acc)[2][2][4][2], const pg8::Unit& u, int wr, int wc, int fr, int fq) const {
;         const int row0 = u.pm * 256 + wr * 64 + fr, col0 = u.pn * 256 + wc * 32 + 8 * fq;
; #pragma unroll
;         for (int ai = 0; ai < 2; ++ai)
; #pragma unroll
;             for (int m = 0; m < 4; ++m) { const int row = row0 + ai * 128 + m * 16; const float rs = rsqrtf(ss_total(ss, row) * (1.f / 1024.f) + EPS);
;                 bf16_t* rowp = O + (size_t)row * ldc + col0;
; #pragma unroll
;                 for (int bj = 0; bj < 2; ++bj) { const f32x4 v0 = acc[ai][bj][m][0] * rs, v1 = acc[ai][bj][m][1] * rs;
;                     u32x4 w; w.x = pk2(v0[0], v0[1]); w.y = pk2(v0[2], v0[3]); w.z = pk2(v1[0], v1[1]); w.w = pk2(v1[2], v1[3]);
;                     *(u32x4*)(rowp + bj * 128) = w; } }
;     }
.Lp1_epi_nt:
	v_lshl_add_u32 v246, s83, 8, v159
	v_lshl_or_b32 v247, s82, 8, v161
	v_lshlrev_b32_e32 v152, 6, v246
	v_mov_b32_e32 v153, 0
	v_lshl_add_u64 v[152:153], s[22:23], 0, v[152:153]
	s_mov_b32 s4, 0x3a00
	v_mul_lo_u32 v164, v246, s4
	v_lshl_add_u32 v164, v247, 1, v164
	v_mov_b32_e32 v165, 0
	v_lshl_add_u64 v[154:155], s[14:15], 0, v[164:165]
	global_load_dwordx4 v[164:167], v[152:153], off
	global_load_dwordx4 v[168:171], v[152:153], off offset:16
	global_load_dwordx4 v[172:175], v[152:153], off offset:32
	global_load_dwordx4 v[176:179], v[152:153], off offset:48
	s_mov_b64 s[4:5], 0x400
	v_lshl_add_u64 v[152:153], v[152:153], 0, s[4:5]
	global_load_dwordx4 v[180:183], v[152:153], off
	global_load_dwordx4 v[184:187], v[152:153], off offset:16
	global_load_dwordx4 v[204:207], v[152:153], off offset:32
	global_load_dwordx4 v[208:211], v[152:153], off offset:48
	s_mov_b64 s[4:5], 0x400
	v_lshl_add_u64 v[152:153], v[152:153], 0, s[4:5]
	global_load_dwordx4 v[212:215], v[152:153], off
	global_load_dwordx4 v[216:219], v[152:153], off offset:16
	global_load_dwordx4 v[220:223], v[152:153], off offset:32
	global_load_dwordx4 v[224:227], v[152:153], off offset:48
	s_mov_b64 s[4:5], 0x400
	v_lshl_add_u64 v[152:153], v[152:153], 0, s[4:5]
	global_load_dwordx4 v[228:231], v[152:153], off
	global_load_dwordx4 v[232:235], v[152:153], off offset:16
	global_load_dwordx4 v[236:239], v[152:153], off offset:32
	global_load_dwordx4 v[240:243], v[152:153], off offset:48
	s_mov_b64 s[4:5], 0x1400
	v_lshl_add_u64 v[152:153], v[152:153], 0, s[4:5]
	s_waitcnt vmcnt(0)
	v_add_f32_e32 v164, v164, v165
	v_add_f32_e32 v168, v168, v169
	v_add_f32_e32 v172, v172, v173
	v_add_f32_e32 v176, v176, v177
	v_add_f32_e32 v166, v166, v167
	v_add_f32_e32 v170, v170, v171
	v_add_f32_e32 v174, v174, v175
	v_add_f32_e32 v178, v178, v179
	v_add_f32_e32 v164, v164, v166
	v_add_f32_e32 v168, v168, v170
	v_add_f32_e32 v172, v172, v174
	v_add_f32_e32 v176, v176, v178
	v_add_f32_e32 v164, v164, v168
	v_add_f32_e32 v172, v172, v176
	v_add_f32_e32 v164, v164, v172
	v_fmamk_f32 v164, v164, 0x3a800000, v190
	v_cmp_gt_f32_e32 vcc, s66, v164
	v_mul_f32_e32 v245, 0x4b800000, v164
	s_nop 1
	v_cndmask_b32_e32 v164, v164, v245, vcc
	v_rsq_f32_e32 v164, v164
	s_nop 0
	v_mul_f32_e32 v245, 0x45800000, v164
	v_cndmask_b32_e32 v156, v164, v245, vcc
	v_add_f32_e32 v180, v180, v181
	v_add_f32_e32 v184, v184, v185
	v_add_f32_e32 v204, v204, v205
	v_add_f32_e32 v208, v208, v209
	v_add_f32_e32 v182, v182, v183
	v_add_f32_e32 v186, v186, v187
	v_add_f32_e32 v206, v206, v207
	v_add_f32_e32 v210, v210, v211
	v_add_f32_e32 v180, v180, v182
	v_add_f32_e32 v184, v184, v186
	v_add_f32_e32 v204, v204, v206
	v_add_f32_e32 v208, v208, v210
	v_add_f32_e32 v180, v180, v184
	v_add_f32_e32 v204, v204, v208
	v_add_f32_e32 v180, v180, v204
	v_fmamk_f32 v180, v180, 0x3a800000, v190
	v_cmp_gt_f32_e32 vcc, s66, v180
	v_mul_f32_e32 v245, 0x4b800000, v180
	s_nop 1
	v_cndmask_b32_e32 v180, v180, v245, vcc
	v_rsq_f32_e32 v180, v180
	s_nop 0
	v_mul_f32_e32 v245, 0x45800000, v180
	v_cndmask_b32_e32 v157, v180, v245, vcc
	v_add_f32_e32 v212, v212, v213
	v_add_f32_e32 v216, v216, v217
	v_add_f32_e32 v220, v220, v221
	v_add_f32_e32 v224, v224, v225
	v_add_f32_e32 v214, v214, v215
	v_add_f32_e32 v218, v218, v219
	v_add_f32_e32 v222, v222, v223
	v_add_f32_e32 v226, v226, v227
	v_add_f32_e32 v212, v212, v214
	v_add_f32_e32 v216, v216, v218
	v_add_f32_e32 v220, v220, v222
	v_add_f32_e32 v224, v224, v226
	v_add_f32_e32 v212, v212, v216
	v_add_f32_e32 v220, v220, v224
	v_add_f32_e32 v212, v212, v220
	v_fmamk_f32 v212, v212, 0x3a800000, v190
	v_cmp_gt_f32_e32 vcc, s66, v212
	v_mul_f32_e32 v245, 0x4b800000, v212
	s_nop 1
	v_cndmask_b32_e32 v212, v212, v245, vcc
	v_rsq_f32_e32 v212, v212
	s_nop 0
	v_mul_f32_e32 v245, 0x45800000, v212
	v_cndmask_b32_e32 v163, v212, v245, vcc
	v_add_f32_e32 v228, v228, v229
	v_add_f32_e32 v232, v232, v233
	v_add_f32_e32 v236, v236, v237
	v_add_f32_e32 v240, v240, v241
	v_add_f32_e32 v230, v230, v231
	v_add_f32_e32 v234, v234, v235
	v_add_f32_e32 v238, v238, v239
	v_add_f32_e32 v242, v242, v243
	v_add_f32_e32 v228, v228, v230
	v_add_f32_e32 v232, v232, v234
	v_add_f32_e32 v236, v236, v238
	v_add_f32_e32 v240, v240, v242
	v_add_f32_e32 v228, v228, v232
	v_add_f32_e32 v236, v236, v240
	v_add_f32_e32 v228, v228, v236
	v_fmamk_f32 v228, v228, 0x3a800000, v190
	v_cmp_gt_f32_e32 vcc, s66, v228
	v_mul_f32_e32 v245, 0x4b800000, v228
	s_nop 1
	v_cndmask_b32_e32 v228, v228, v245, vcc
	v_rsq_f32_e32 v228, v228
	s_nop 0
	v_mul_f32_e32 v245, 0x45800000, v228
	v_cndmask_b32_e32 v244, v228, v245, vcc
	global_load_dwordx4 v[164:167], v[152:153], off
	global_load_dwordx4 v[168:171], v[152:153], off offset:16
	global_load_dwordx4 v[172:175], v[152:153], off offset:32
	global_load_dwordx4 v[176:179], v[152:153], off offset:48
	s_mov_b64 s[4:5], 0x400
	v_lshl_add_u64 v[152:153], v[152:153], 0, s[4:5]
	global_load_dwordx4 v[180:183], v[152:153], off
	global_load_dwordx4 v[184:187], v[152:153], off offset:16
	global_load_dwordx4 v[204:207], v[152:153], off offset:32
	global_load_dwordx4 v[208:211], v[152:153], off offset:48
	s_mov_b64 s[4:5], 0x400
	v_lshl_add_u64 v[152:153], v[152:153], 0, s[4:5]
	global_load_dwordx4 v[212:215], v[152:153], off
	global_load_dwordx4 v[216:219], v[152:153], off offset:16
	global_load_dwordx4 v[220:223], v[152:153], off offset:32
	global_load_dwordx4 v[224:227], v[152:153], off offset:48
	s_mov_b64 s[4:5], 0x400
	v_lshl_add_u64 v[152:153], v[152:153], 0, s[4:5]
	global_load_dwordx4 v[228:231], v[152:153], off
	global_load_dwordx4 v[232:235], v[152:153], off offset:16
; __device__ __forceinline__ unsigned pk2(float lo, float hi) { f32x2 v = {lo, hi}; bf16x2_t b = __builtin_convertvector(v, bf16x2_t); return __builtin_bit_cast(unsigned, b); }
;     __device__ __forceinline__ void operator()(const f32x4 (&acc)[2][2][4][2], const pg8::Unit& u, int wr, int wc, int fr, int fq) const {
;         const int row0 = u.pm * 256 + wr * 64 + fr, col0 = u.pn * 256 + wc * 32 + 8 * fq;
; #pragma unroll
;         for (int ai = 0; ai < 2; ++ai)
; #pragma unroll
;             for (int m = 0; m < 4; ++m) { const int row = row0 + ai * 128 + m * 16; const float rs = rsqrtf(ss_total(ss, row) * (1.f / 1024.f) + EPS);
;                 bf16_t* rowp = O + (size_t)row * ldc + col0;
; #pragma unroll
;                 for (int bj = 0; bj < 2; ++bj) { const f32x4 v0 = acc[ai][bj][m][0] * rs, v1 = acc[ai][bj][m][1] * rs;
;                     u32x4 w; w.x = pk2(v0[0], v0[1]); w.y = pk2(v0[2], v0[3]); w.z = pk2(v1[0], v1[1]); w.w = pk2(v1[2], v1[3]);
;                     *(u32x4*)(rowp + bj * 128) = w; } }
;     }
	global_load_dwordx4 v[236:239], v[152:153], off offset:32
	global_load_dwordx4 v[240:243], v[152:153], off offset:48
	v_mul_f32_e32 v126, v126, v156
	v_mul_f32_e32 v127, v127, v156
	v_mul_f32_e32 v128, v128, v156
	v_mul_f32_e32 v129, v129, v156
	v_mul_f32_e32 v122, v122, v156
	v_mul_f32_e32 v123, v123, v156
	v_mul_f32_e32 v124, v124, v156
	v_mul_f32_e32 v125, v125, v156
	v_cvt_pk_bf16_f32 v126, v126, v127
	v_cvt_pk_bf16_f32 v127, v128, v129
	v_cvt_pk_bf16_f32 v128, v122, v123
	v_cvt_pk_bf16_f32 v129, v124, v125
	global_store_dwordx4 v[154:155], v[126:129], off nt
	v_mul_f32_e32 v118, v118, v156
	v_mul_f32_e32 v119, v119, v156
	v_mul_f32_e32 v120, v120, v156
	v_mul_f32_e32 v121, v121, v156
	v_mul_f32_e32 v114, v114, v156
	v_mul_f32_e32 v115, v115, v156
	v_mul_f32_e32 v116, v116, v156
	v_mul_f32_e32 v117, v117, v156
	v_cvt_pk_bf16_f32 v118, v118, v119
	v_cvt_pk_bf16_f32 v119, v120, v121
	v_cvt_pk_bf16_f32 v120, v114, v115
	v_cvt_pk_bf16_f32 v121, v116, v117
	global_store_dwordx4 v[154:155], v[118:121], off offset:256 nt
	s_mov_b64 s[4:5], 0x3a000
	v_lshl_add_u64 v[154:155], v[154:155], 0, s[4:5]
	v_mul_f32_e32 v110, v110, v157
	v_mul_f32_e32 v111, v111, v157
	v_mul_f32_e32 v112, v112, v157
	v_mul_f32_e32 v113, v113, v157
	v_mul_f32_e32 v106, v106, v157
	v_mul_f32_e32 v107, v107, v157
	v_mul_f32_e32 v108, v108, v157
	v_mul_f32_e32 v109, v109, v157
	v_cvt_pk_bf16_f32 v110, v110, v111
	v_cvt_pk_bf16_f32 v111, v112, v113
	v_cvt_pk_bf16_f32 v112, v106, v107
	v_cvt_pk_bf16_f32 v113, v108, v109
	global_store_dwordx4 v[154:155], v[110:113], off nt
	v_mul_f32_e32 v102, v102, v157
	v_mul_f32_e32 v103, v103, v157
	v_mul_f32_e32 v104, v104, v157
	v_mul_f32_e32 v105, v105, v157
	v_mul_f32_e32 v98, v98, v157
	v_mul_f32_e32 v99, v99, v157
	v_mul_f32_e32 v100, v100, v157
	v_mul_f32_e32 v101, v101, v157
	v_cvt_pk_bf16_f32 v102, v102, v103
	v_cvt_pk_bf16_f32 v103, v104, v105
	v_cvt_pk_bf16_f32 v104, v98, v99
	v_cvt_pk_bf16_f32 v105, v100, v101
	global_store_dwordx4 v[154:155], v[102:105], off offset:256 nt
	s_mov_b64 s[4:5], 0x3a000
	v_lshl_add_u64 v[154:155], v[154:155], 0, s[4:5]
	v_mul_f32_e32 v94, v94, v163
	v_mul_f32_e32 v95, v95, v163
	v_mul_f32_e32 v96, v96, v163
	v_mul_f32_e32 v97, v97, v163
	v_mul_f32_e32 v90, v90, v163
	v_mul_f32_e32 v91, v91, v163
	v_mul_f32_e32 v92, v92, v163
	v_mul_f32_e32 v93, v93, v163
	v_cvt_pk_bf16_f32 v94, v94, v95
	v_cvt_pk_bf16_f32 v95, v96, v97
	v_cvt_pk_bf16_f32 v96, v90, v91
	v_cvt_pk_bf16_f32 v97, v92, v93
	global_store_dwordx4 v[154:155], v[94:97], off nt
	v_mul_f32_e32 v86, v86, v163
	v_mul_f32_e32 v87, v87, v163
	v_mul_f32_e32 v88, v88, v163
	v_mul_f32_e32 v89, v89, v163
	v_mul_f32_e32 v82, v82, v163
	v_mul_f32_e32 v83, v83, v163
	v_mul_f32_e32 v84, v84, v163
	v_mul_f32_e32 v85, v85, v163
	v_cvt_pk_bf16_f32 v86, v86, v87
	v_cvt_pk_bf16_f32 v87, v88, v89
	v_cvt_pk_bf16_f32 v88, v82, v83
	v_cvt_pk_bf16_f32 v89, v84, v85
	global_store_dwordx4 v[154:155], v[86:89], off offset:256 nt
	s_mov_b64 s[4:5], 0x3a000
	v_lshl_add_u64 v[154:155], v[154:155], 0, s[4:5]
	v_mul_f32_e32 v78, v78, v244
	v_mul_f32_e32 v79, v79, v244
	v_mul_f32_e32 v80, v80, v244
	v_mul_f32_e32 v81, v81, v244
	v_mul_f32_e32 v74, v74, v244
	v_mul_f32_e32 v75, v75, v244
	v_mul_f32_e32 v76, v76, v244
	v_mul_f32_e32 v77, v77, v244
	v_cvt_pk_bf16_f32 v78, v78, v79
	v_cvt_pk_bf16_f32 v79, v80, v81
	v_cvt_pk_bf16_f32 v80, v74, v75
	v_cvt_pk_bf16_f32 v81, v76, v77
	global_store_dwordx4 v[154:155], v[78:81], off nt
	v_mul_f32_e32 v70, v70, v244
	v_mul_f32_e32 v71, v71, v244
	v_mul_f32_e32 v72, v72, v244
	v_mul_f32_e32 v73, v73, v244
	v_mul_f32_e32 v66, v66, v244
	v_mul_f32_e32 v67, v67, v244
	v_mul_f32_e32 v68, v68, v244
	v_mul_f32_e32 v69, v69, v244
	v_cvt_pk_bf16_f32 v70, v70, v71
	v_cvt_pk_bf16_f32 v71, v72, v73
	v_cvt_pk_bf16_f32 v72, v66, v67
	v_cvt_pk_bf16_f32 v73, v68, v69
	global_store_dwordx4 v[154:155], v[70:73], off offset:256 nt
	s_mov_b64 s[4:5], 0x122000
	v_lshl_add_u64 v[154:155], v[154:155], 0, s[4:5]
	s_waitcnt vmcnt(8)
; __device__ __forceinline__ unsigned pk2(float lo, float hi) { f32x2 v = {lo, hi}; bf16x2_t b = __builtin_convertvector(v, bf16x2_t); return __builtin_bit_cast(unsigned, b); }
; __device__ __forceinline__ float ss_total(const float* ss, int row) { const f32x4* sp = (const f32x4*)(ss + (size_t)row * 16); const f32x4 a = sp[0], b = sp[1], c = sp[2], d = sp[3];
;     return (((a[0] + a[1]) + (a[2] + a[3])) + ((b[0] + b[1]) + (b[2] + b[3]))) + (((c[0] + c[1]) + (c[2] + c[3])) + ((d[0] + d[1]) + (d[2] + d[3]))); }
;     __device__ __forceinline__ void operator()(const f32x4 (&acc)[2][2][4][2], const pg8::Unit& u, int wr, int wc, int fr, int fq) const {
;         const int row0 = u.pm * 256 + wr * 64 + fr, col0 = u.pn * 256 + wc * 32 + 8 * fq;
; #pragma unroll
;         for (int ai = 0; ai < 2; ++ai)
; #pragma unroll
;             for (int m = 0; m < 4; ++m) { const int row = row0 + ai * 128 + m * 16; const float rs = rsqrtf(ss_total(ss, row) * (1.f / 1024.f) + EPS);
;                 bf16_t* rowp = O + (size_t)row * ldc + col0;
; #pragma unroll
;                 for (int bj = 0; bj < 2; ++bj) { const f32x4 v0 = acc[ai][bj][m][0] * rs, v1 = acc[ai][bj][m][1] * rs;
;                     u32x4 w; w.x = pk2(v0[0], v0[1]); w.y = pk2(v0[2], v0[3]); w.z = pk2(v1[0], v1[1]); w.w = pk2(v1[2], v1[3]);
;                     *(u32x4*)(rowp + bj * 128) = w; } }
;     }
	v_add_f32_e32 v164, v164, v165
	v_add_f32_e32 v168, v168, v169
	v_add_f32_e32 v172, v172, v173
	v_add_f32_e32 v176, v176, v177
	v_add_f32_e32 v166, v166, v167
	v_add_f32_e32 v170, v170, v171
	v_add_f32_e32 v174, v174, v175
	v_add_f32_e32 v178, v178, v179
	v_add_f32_e32 v164, v164, v166
	v_add_f32_e32 v168, v168, v170
	v_add_f32_e32 v172, v172, v174
	v_add_f32_e32 v176, v176, v178
	v_add_f32_e32 v164, v164, v168
	v_add_f32_e32 v172, v172, v176
	v_add_f32_e32 v164, v164, v172
	v_fmamk_f32 v164, v164, 0x3a800000, v190
	v_cmp_gt_f32_e32 vcc, s66, v164
	v_mul_f32_e32 v245, 0x4b800000, v164
	s_nop 1
	v_cndmask_b32_e32 v164, v164, v245, vcc
	v_rsq_f32_e32 v164, v164
	s_nop 0
	v_mul_f32_e32 v245, 0x45800000, v164
	v_cndmask_b32_e32 v156, v164, v245, vcc
	v_add_f32_e32 v180, v180, v181
	v_add_f32_e32 v184, v184, v185
	v_add_f32_e32 v204, v204, v205
	v_add_f32_e32 v208, v208, v209
	v_add_f32_e32 v182, v182, v183
	v_add_f32_e32 v186, v186, v187
	v_add_f32_e32 v206, v206, v207
	v_add_f32_e32 v210, v210, v211
	v_add_f32_e32 v180, v180, v182
	v_add_f32_e32 v184, v184, v186
	v_add_f32_e32 v204, v204, v206
	v_add_f32_e32 v208, v208, v210
	v_add_f32_e32 v180, v180, v184
	v_add_f32_e32 v204, v204, v208
	v_add_f32_e32 v180, v180, v204
	v_fmamk_f32 v180, v180, 0x3a800000, v190
	v_cmp_gt_f32_e32 vcc, s66, v180
	v_mul_f32_e32 v245, 0x4b800000, v180
	s_nop 1
	v_cndmask_b32_e32 v180, v180, v245, vcc
	v_rsq_f32_e32 v180, v180
	s_nop 0
	v_mul_f32_e32 v245, 0x45800000, v180
	v_cndmask_b32_e32 v157, v180, v245, vcc
	v_add_f32_e32 v212, v212, v213
	v_add_f32_e32 v216, v216, v217
	v_add_f32_e32 v220, v220, v221
	v_add_f32_e32 v224, v224, v225
	v_add_f32_e32 v214, v214, v215
	v_add_f32_e32 v218, v218, v219
	v_add_f32_e32 v222, v222, v223
	v_add_f32_e32 v226, v226, v227
	v_add_f32_e32 v212, v212, v214
	v_add_f32_e32 v216, v216, v218
	v_add_f32_e32 v220, v220, v222
	v_add_f32_e32 v224, v224, v226
	v_add_f32_e32 v212, v212, v216
	v_add_f32_e32 v220, v220, v224
	v_add_f32_e32 v212, v212, v220
	v_fmamk_f32 v212, v212, 0x3a800000, v190
	v_cmp_gt_f32_e32 vcc, s66, v212
	v_mul_f32_e32 v245, 0x4b800000, v212
	s_nop 1
	v_cndmask_b32_e32 v212, v212, v245, vcc
	v_rsq_f32_e32 v212, v212
	s_nop 0
	v_mul_f32_e32 v245, 0x45800000, v212
	v_cndmask_b32_e32 v163, v212, v245, vcc
	v_add_f32_e32 v228, v228, v229
	v_add_f32_e32 v232, v232, v233
	v_add_f32_e32 v236, v236, v237
	v_add_f32_e32 v240, v240, v241
	v_add_f32_e32 v230, v230, v231
	v_add_f32_e32 v234, v234, v235
	v_add_f32_e32 v238, v238, v239
	v_add_f32_e32 v242, v242, v243
	v_add_f32_e32 v228, v228, v230
	v_add_f32_e32 v232, v232, v234
	v_add_f32_e32 v236, v236, v238
	v_add_f32_e32 v240, v240, v242
	v_add_f32_e32 v228, v228, v232
	v_add_f32_e32 v236, v236, v240
	v_add_f32_e32 v228, v228, v236
	v_fmamk_f32 v228, v228, 0x3a800000, v190
	v_cmp_gt_f32_e32 vcc, s66, v228
	v_mul_f32_e32 v245, 0x4b800000, v228
	s_nop 1
	v_cndmask_b32_e32 v228, v228, v245, vcc
	v_rsq_f32_e32 v228, v228
	s_nop 0
	v_mul_f32_e32 v245, 0x45800000, v228
	v_cndmask_b32_e32 v244, v228, v245, vcc
	v_mul_f32_e32 v62, v62, v156
	v_mul_f32_e32 v63, v63, v156
	v_mul_f32_e32 v64, v64, v156
	v_mul_f32_e32 v65, v65, v156
	v_mul_f32_e32 v58, v58, v156
	v_mul_f32_e32 v59, v59, v156
	v_mul_f32_e32 v60, v60, v156
	v_mul_f32_e32 v61, v61, v156
	v_cvt_pk_bf16_f32 v62, v62, v63
	v_cvt_pk_bf16_f32 v63, v64, v65
	v_cvt_pk_bf16_f32 v64, v58, v59
	v_cvt_pk_bf16_f32 v65, v60, v61
	global_store_dwordx4 v[154:155], v[62:65], off nt
	v_mul_f32_e32 v54, v54, v156
	v_mul_f32_e32 v55, v55, v156
	v_mul_f32_e32 v56, v56, v156
	v_mul_f32_e32 v57, v57, v156
	v_mul_f32_e32 v50, v50, v156
	v_mul_f32_e32 v51, v51, v156
	v_mul_f32_e32 v52, v52, v156
	v_mul_f32_e32 v53, v53, v156
	v_cvt_pk_bf16_f32 v54, v54, v55
	v_cvt_pk_bf16_f32 v55, v56, v57
	v_cvt_pk_bf16_f32 v56, v50, v51
	v_cvt_pk_bf16_f32 v57, v52, v53
	global_store_dwordx4 v[154:155], v[54:57], off offset:256 nt
	s_mov_b64 s[4:5], 0x3a000
	v_lshl_add_u64 v[154:155], v[154:155], 0, s[4:5]
	v_mul_f32_e32 v46, v46, v157
	v_mul_f32_e32 v47, v47, v157
	v_mul_f32_e32 v48, v48, v157
	v_mul_f32_e32 v49, v49, v157
	v_mul_f32_e32 v42, v42, v157
	v_mul_f32_e32 v43, v43, v157
	v_mul_f32_e32 v44, v44, v157
	v_mul_f32_e32 v45, v45, v157
	v_cvt_pk_bf16_f32 v46, v46, v47
	v_cvt_pk_bf16_f32 v47, v48, v49
	v_cvt_pk_bf16_f32 v48, v42, v43
	v_cvt_pk_bf16_f32 v49, v44, v45
	global_store_dwordx4 v[154:155], v[46:49], off nt
	v_mul_f32_e32 v38, v38, v157
	v_mul_f32_e32 v39, v39, v157
	v_mul_f32_e32 v40, v40, v157
	v_mul_f32_e32 v41, v41, v157
	v_mul_f32_e32 v34, v34, v157
	v_mul_f32_e32 v35, v35, v157
	v_mul_f32_e32 v36, v36, v157
	v_mul_f32_e32 v37, v37, v157
	v_cvt_pk_bf16_f32 v38, v38, v39
	v_cvt_pk_bf16_f32 v39, v40, v41
	v_cvt_pk_bf16_f32 v40, v34, v35
	v_cvt_pk_bf16_f32 v41, v36, v37
	global_store_dwordx4 v[154:155], v[38:41], off offset:256 nt
	s_mov_b64 s[4:5], 0x3a000
	v_lshl_add_u64 v[154:155], v[154:155], 0, s[4:5]
	v_mul_f32_e32 v30, v30, v163
	v_mul_f32_e32 v31, v31, v163
	v_mul_f32_e32 v32, v32, v163
	v_mul_f32_e32 v33, v33, v163
	v_mul_f32_e32 v26, v26, v163
	v_mul_f32_e32 v27, v27, v163
	v_mul_f32_e32 v28, v28, v163
	v_mul_f32_e32 v29, v29, v163
	v_cvt_pk_bf16_f32 v30, v30, v31
	v_cvt_pk_bf16_f32 v31, v32, v33
	v_cvt_pk_bf16_f32 v32, v26, v27
	v_cvt_pk_bf16_f32 v33, v28, v29
	global_store_dwordx4 v[154:155], v[30:33], off nt
	v_mul_f32_e32 v22, v22, v163
	v_mul_f32_e32 v23, v23, v163
	v_mul_f32_e32 v24, v24, v163
	v_mul_f32_e32 v25, v25, v163
	v_mul_f32_e32 v18, v18, v163
	v_mul_f32_e32 v19, v19, v163
	v_mul_f32_e32 v20, v20, v163
	v_mul_f32_e32 v21, v21, v163
	v_cvt_pk_bf16_f32 v22, v22, v23
	v_cvt_pk_bf16_f32 v23, v24, v25
	v_cvt_pk_bf16_f32 v24, v18, v19
	v_cvt_pk_bf16_f32 v25, v20, v21
	global_store_dwordx4 v[154:155], v[22:25], off offset:256 nt
	s_mov_b64 s[4:5], 0x3a000
	v_lshl_add_u64 v[154:155], v[154:155], 0, s[4:5]
	v_mul_f32_e32 v14, v14, v244
	v_mul_f32_e32 v15, v15, v244
	v_mul_f32_e32 v16, v16, v244
	v_mul_f32_e32 v17, v17, v244
	v_mul_f32_e32 v10, v10, v244
	v_mul_f32_e32 v11, v11, v244
	v_mul_f32_e32 v12, v12, v244
	v_mul_f32_e32 v13, v13, v244
	v_cvt_pk_bf16_f32 v14, v14, v15
	v_cvt_pk_bf16_f32 v15, v16, v17
	v_cvt_pk_bf16_f32 v16, v10, v11
	v_cvt_pk_bf16_f32 v17, v12, v13
	global_store_dwordx4 v[154:155], v[14:17], off nt
	v_mul_f32_e32 v6, v6, v244
	v_mul_f32_e32 v7, v7, v244
	v_mul_f32_e32 v8, v8, v244
	v_mul_f32_e32 v9, v9, v244
	v_mul_f32_e32 v2, v2, v244
	v_mul_f32_e32 v3, v3, v244
	v_mul_f32_e32 v4, v4, v244
	v_mul_f32_e32 v5, v5, v244
	v_cvt_pk_bf16_f32 v6, v6, v7
	v_cvt_pk_bf16_f32 v7, v8, v9
	v_cvt_pk_bf16_f32 v8, v2, v3
	v_cvt_pk_bf16_f32 v9, v4, v5
	global_store_dwordx4 v[154:155], v[6:9], off offset:256 nt
	v_readlane_b32 s84, v250, 44
	s_mov_b64 s[4:5], -1
	s_andn2_b64 vcc, exec, s[38:39]
	s_branch .Lp1_epi_join
